# FOX attention epilogue: output staged through wave-private LDS, 4 global_store_dwordx4 per lane instead of 32 global_store_short
# baseline (speedup 1.0000x reference)
.LBB0_834:
	s_setprio 0
	s_lshr_b32 s6, s2, 11
	s_lshl_b32 s6, s6, 14
	s_and_b32 s7, s2, 0x400
	s_lshl_b32 s7, s7, 2
	s_add_i32 s6, s6, s7
	s_add_i32 s6, s6, 0x2000
	v_lshlrev_b32_e32 v0, 9, v135
	v_lshl_add_u32 v0, v136, 1, v0
	v_add_u32_e32 v0, s6, v0
	v_lshl_add_u32 v10, v135, 5, v136
	v_lshlrev_b32_e32 v11, 4, v10
	v_add_u32_e32 v11, s6, v11
	v_rcp_f32_e32 v80, v62
	v_rcp_f32_e32 v81, v63
	v_rcp_f32_e32 v82, v64
	v_rcp_f32_e32 v83, v65
	v_rcp_f32_e32 v84, v66
	v_rcp_f32_e32 v85, v67
	v_rcp_f32_e32 v86, v68
	v_rcp_f32_e32 v87, v69
	v_rcp_f32_e32 v88, v70
	v_rcp_f32_e32 v89, v71
	v_rcp_f32_e32 v90, v72
	v_rcp_f32_e32 v91, v73
	v_rcp_f32_e32 v92, v74
	v_rcp_f32_e32 v93, v75
	v_rcp_f32_e32 v94, v76
	v_rcp_f32_e32 v95, v77
	v_mul_f32_e32 v2, v32, v80
	v_cvt_pk_bf16_f32 v2, v2, s0
	ds_write_b16 v0, v2
	v_mul_f32_e32 v3, v16, v80
	v_cvt_pk_bf16_f32 v3, v3, s0
	ds_write_b16 v0, v3 offset:64
	v_mul_f32_e32 v4, v33, v81
	v_cvt_pk_bf16_f32 v4, v4, s0
	ds_write_b16 v0, v4 offset:128
	v_mul_f32_e32 v5, v17, v81
	v_cvt_pk_bf16_f32 v5, v5, s0
	ds_write_b16 v0, v5 offset:192
	v_mul_f32_e32 v6, v34, v82
	v_cvt_pk_bf16_f32 v6, v6, s0
	ds_write_b16 v0, v6 offset:256
	v_mul_f32_e32 v7, v18, v82
	v_cvt_pk_bf16_f32 v7, v7, s0
	ds_write_b16 v0, v7 offset:320
	v_mul_f32_e32 v8, v35, v83
	v_cvt_pk_bf16_f32 v8, v8, s0
	ds_write_b16 v0, v8 offset:384
	v_mul_f32_e32 v9, v19, v83
	v_cvt_pk_bf16_f32 v9, v9, s0
	ds_write_b16 v0, v9 offset:448
	v_mul_f32_e32 v2, v36, v84
	v_cvt_pk_bf16_f32 v2, v2, s0
	ds_write_b16 v0, v2 offset:1024
	v_mul_f32_e32 v3, v20, v84
	v_cvt_pk_bf16_f32 v3, v3, s0
	ds_write_b16 v0, v3 offset:1088
	v_mul_f32_e32 v4, v37, v85
	v_cvt_pk_bf16_f32 v4, v4, s0
	ds_write_b16 v0, v4 offset:1152
	v_mul_f32_e32 v5, v21, v85
	v_cvt_pk_bf16_f32 v5, v5, s0
	ds_write_b16 v0, v5 offset:1216
	v_mul_f32_e32 v6, v38, v86
	v_cvt_pk_bf16_f32 v6, v6, s0
	ds_write_b16 v0, v6 offset:1280
	v_mul_f32_e32 v7, v22, v86
	v_cvt_pk_bf16_f32 v7, v7, s0
	ds_write_b16 v0, v7 offset:1344
	v_mul_f32_e32 v8, v39, v87
	v_cvt_pk_bf16_f32 v8, v8, s0
	ds_write_b16 v0, v8 offset:1408
	v_mul_f32_e32 v9, v23, v87
	v_cvt_pk_bf16_f32 v9, v9, s0
	ds_write_b16 v0, v9 offset:1472
	v_mul_f32_e32 v2, v40, v88
	v_cvt_pk_bf16_f32 v2, v2, s0
	ds_write_b16 v0, v2 offset:2048
	v_mul_f32_e32 v3, v24, v88
	v_cvt_pk_bf16_f32 v3, v3, s0
	ds_write_b16 v0, v3 offset:2112
	v_mul_f32_e32 v4, v41, v89
	v_cvt_pk_bf16_f32 v4, v4, s0
	ds_write_b16 v0, v4 offset:2176
	v_mul_f32_e32 v5, v25, v89
	v_cvt_pk_bf16_f32 v5, v5, s0
	ds_write_b16 v0, v5 offset:2240
	v_mul_f32_e32 v6, v42, v90
	v_cvt_pk_bf16_f32 v6, v6, s0
	ds_write_b16 v0, v6 offset:2304
	v_mul_f32_e32 v7, v26, v90
	v_cvt_pk_bf16_f32 v7, v7, s0
	ds_write_b16 v0, v7 offset:2368
	v_mul_f32_e32 v8, v43, v91
	v_cvt_pk_bf16_f32 v8, v8, s0
	ds_write_b16 v0, v8 offset:2432
	v_mul_f32_e32 v9, v27, v91
	v_cvt_pk_bf16_f32 v9, v9, s0
	ds_write_b16 v0, v9 offset:2496
	v_mul_f32_e32 v2, v44, v92
	v_cvt_pk_bf16_f32 v2, v2, s0
	ds_write_b16 v0, v2 offset:3072
	v_mul_f32_e32 v3, v28, v92
	v_cvt_pk_bf16_f32 v3, v3, s0
	ds_write_b16 v0, v3 offset:3136
	v_mul_f32_e32 v4, v45, v93
	v_cvt_pk_bf16_f32 v4, v4, s0
	ds_write_b16 v0, v4 offset:3200
	v_mul_f32_e32 v5, v29, v93
	v_cvt_pk_bf16_f32 v5, v5, s0
	ds_write_b16 v0, v5 offset:3264
	v_mul_f32_e32 v6, v46, v94
	v_cvt_pk_bf16_f32 v6, v6, s0
	ds_write_b16 v0, v6 offset:3328
	v_mul_f32_e32 v7, v30, v94
	v_cvt_pk_bf16_f32 v7, v7, s0
	ds_write_b16 v0, v7 offset:3392
	v_mul_f32_e32 v8, v47, v95
	v_cvt_pk_bf16_f32 v8, v8, s0
	ds_write_b16 v0, v8 offset:3456
	v_mul_f32_e32 v9, v31, v95
	v_cvt_pk_bf16_f32 v9, v9, s0
	ds_write_b16 v0, v9 offset:3520
	s_lshl_b64 s[6:7], s[74:75], 11
	s_add_u32 s6, s94, s6
	s_addc_u32 s7, s95, s7
	s_add_u32 s6, s6, s3
	s_addc_u32 s7, s7, 0
	v_lshrrev_b32_e32 v12, 3, v10
	v_lshlrev_b32_e32 v12, 11, v12
	v_and_b32_e32 v13, 7, v10
	v_lshl_add_u32 v12, v13, 4, v12
	v_mov_b32_e32 v13, 0
	v_lshl_add_u64 v[12:13], s[6:7], 0, v[12:13]
	s_mov_b64 s[8:9], 0x4000
	s_waitcnt lgkmcnt(0)
	ds_read_b128 v[96:99], v11
	ds_read_b128 v[100:103], v11 offset:1024
	ds_read_b128 v[104:107], v11 offset:2048
	ds_read_b128 v[108:111], v11 offset:3072
	v_lshl_add_u64 v[14:15], v[12:13], 0, s[8:9]
	s_waitcnt lgkmcnt(3)
	global_store_dwordx4 v[12:13], v[96:99], off offset:1024
	v_lshl_add_u64 v[2:3], v[14:15], 0, s[8:9]
	s_waitcnt lgkmcnt(2)
	global_store_dwordx4 v[14:15], v[100:103], off offset:1024
	v_lshl_add_u64 v[4:5], v[2:3], 0, s[8:9]
	s_waitcnt lgkmcnt(1)
	global_store_dwordx4 v[2:3], v[104:107], off offset:1024
	s_waitcnt lgkmcnt(0)
	global_store_dwordx4 v[4:5], v[108:111], off offset:1024
	s_barrier
